# GEMM2 gate epilogue: all gate loads of a half tile issued before one wait (hipcc had serialized them with a wait after each load)
# speedup vs baseline: 1.0114x; 1.0017x over previous
; #define PG8_STAGE(bufoff, gbase, voff) do { _Pragma("unroll") for (int _i = 0; _i < 2; ++_i) \
;         __builtin_amdgcn_global_load_lds((const unsigned*)((const char*)(gbase) + (voff)[_i]), (LAS unsigned*)(lds + (bufoff) + ldsw + _i * 8192), 16, 0, 0); } while (0)
; #define PG8_LDA(dst, b, h) do { _Pragma("unroll") for (int m = 0; m < 4; ++m) _Pragma("unroll") for (int k = 0; k < 2; ++k) dst[m][k] = *(const LAS bf16x8*)(lds + PG8_SA(b, h) + aoff + m * 2048 + k * 1024); } while (0)
; #define PG8_LDB(dst, b, h) do { _Pragma("unroll") for (int n = 0; n < 2; ++n) _Pragma("unroll") for (int k = 0; k < 2; ++k) dst[n][k] = *(const LAS bf16x8*)(lds + PG8_SB(b, h) + boff + n * 2048 + k * 1024); } while (0)
; #define PG8_MMA(ai, bj, At, Bt) do { __builtin_amdgcn_s_setprio(1); _Pragma("unroll") for (int m = 0; m < 4; ++m) _Pragma("unroll") for (int n = 0; n < 2; ++n) _Pragma("unroll") for (int k = 0; k < 2; ++k) \
;         acc[ai][bj][m][n] = __builtin_amdgcn_mfma_f32_16x16x32_bf16(Bt[n][k], At[m][k], acc[ai][bj][m][n], 0, 0, 0); __builtin_amdgcn_s_setprio(0); } while (0)
; #define PG8_WAIT_V(n) asm volatile("s_waitcnt vmcnt(" #n ")" ::: "memory")
; #define PG8_WAIT_L(n) asm volatile("s_waitcnt lgkmcnt(" #n ")" ::: "memory")
; #define PG8_BAR __builtin_amdgcn_s_barrier()
; #define PG8_SCHED __builtin_amdgcn_sched_barrier(0)
; template <class Epi, class Sched>
; DI void gemm_phase(LAS unsigned char* lds, const Gemm g, const Sched& S, const Epi& E) {
;     ...
;             PG8_LDB(B0, 0, 0); PG8_SCHED; PG8_LDA(At, 0, 0); PG8_STAGE(PG8_SA(1, 1), a1 + hstep, voffA);
;             PG8_WAIT_L(8); PG8_BAR; PG8_WAIT_L(0); PG8_MMA(0, 0, At, B0); PG8_BAR; PG8_SCHED;
;             PG8_LDB(B1, 0, 1); PG8_STAGE(PG8_SB(0, 0), b2, voffB);
;             PG8_BAR; PG8_WAIT_L(0); PG8_MMA(0, 1, At, B1); PG8_BAR;
;             PG8_LDA(At, 0, 1); PG8_STAGE(PG8_SA(0, 0), a2, voffA);
;             PG8_BAR; PG8_WAIT_L(0); PG8_MMA(1, 0, At, B0); PG8_BAR; PG8_SCHED;
;             PG8_STAGE(PG8_SB(0, 1), b2 + hstep, voffB);
;             PG8_WAIT_V(6); PG8_BAR; PG8_MMA(1, 1, At, B1); PG8_BAR;
.LBB0_726:
	v_add_u32_e32 v1, s47, v226
	s_waitcnt vmcnt(0)
	ds_read_b128 v[132:135], v1
	ds_read_b128 v[136:139], v1 offset:1024
	ds_read_b128 v[140:143], v1 offset:2048
	ds_read_b128 v[144:147], v1 offset:3072
	s_add_u32 s26, s24, 0xfff80080
	s_addc_u32 s27, s25, -1
	s_cmp_eq_u32 s64, 28
	s_cselect_b32 s29, s5, s27
	s_cselect_b32 s28, s19, s26
	s_cselect_b32 s27, s17, s63
	s_cselect_b32 s26, s30, s31
	v_lshl_add_u64 v[2:3], s[24:25], 0, v[208:209]
	s_add_i32 m0, s42, 0xc000
	ds_read_b128 v[148:151], v228
	ds_read_b128 v[152:155], v228 offset:1024
	ds_read_b128 v[156:159], v228 offset:2048
	ds_read_b128 v[160:163], v228 offset:3072
	ds_read_b128 v[164:167], v228 offset:4096
	ds_read_b128 v[168:171], v228 offset:5120
	ds_read_b128 v[172:175], v228 offset:6144
	ds_read_b128 v[176:179], v228 offset:7168
	global_load_lds_dwordx4 v[2:3], off
	v_lshl_add_u64 v[2:3], s[24:25], 0, v[210:211]
	s_add_i32 m0, s42, 0xe000
	s_nop 0
	global_load_lds_dwordx4 v[2:3], off
	s_waitcnt lgkmcnt(8)
	s_barrier
	s_waitcnt lgkmcnt(0)
	s_setprio 1
	s_waitcnt lgkmcnt(0)
	v_mfma_f32_16x16x32_bf16 v[32:35], v[132:135], v[148:151], v[32:35]
	v_mfma_f32_16x16x32_bf16 v[28:31], v[140:143], v[148:151], v[28:31]
	v_mfma_f32_16x16x32_bf16 v[24:27], v[132:135], v[156:159], v[24:27]
	v_mfma_f32_16x16x32_bf16 v[20:23], v[140:143], v[156:159], v[20:23]
	v_mfma_f32_16x16x32_bf16 v[16:19], v[132:135], v[164:167], v[16:19]
	v_mfma_f32_16x16x32_bf16 v[12:15], v[140:143], v[164:167], v[12:15]
	v_mfma_f32_16x16x32_bf16 v[8:11], v[132:135], v[172:175], v[8:11]
	v_mfma_f32_16x16x32_bf16 v[2:5], v[140:143], v[172:175], v[4:7]
	v_mfma_f32_16x16x32_bf16 v[32:35], v[136:139], v[152:155], v[32:35]
	v_mfma_f32_16x16x32_bf16 v[28:31], v[144:147], v[152:155], v[28:31]
	v_mfma_f32_16x16x32_bf16 v[24:27], v[136:139], v[160:163], v[24:27]
	v_mfma_f32_16x16x32_bf16 v[20:23], v[144:147], v[160:163], v[20:23]
	v_mfma_f32_16x16x32_bf16 v[16:19], v[136:139], v[168:171], v[16:19]
	v_mfma_f32_16x16x32_bf16 v[12:15], v[144:147], v[168:171], v[12:15]
	v_mfma_f32_16x16x32_bf16 v[8:11], v[136:139], v[176:179], v[8:11]
	v_mfma_f32_16x16x32_bf16 v[2:5], v[144:147], v[176:179], v[2:5]
	s_setprio 0
	s_barrier
	s_add_i32 s65, s47, s41
	v_add_u32_e32 v1, s60, v226
	v_lshl_add_u64 v[216:217], s[26:27], 0, v[200:201]
	s_mov_b32 m0, s65
	ds_read_b128 v[180:183], v1
	ds_read_b128 v[184:187], v1 offset:1024
	ds_read_b128 v[188:191], v1 offset:2048
	ds_read_b128 v[192:195], v1 offset:3072
	global_load_lds_dwordx4 v[216:217], off
	v_lshl_add_u64 v[218:219], s[26:27], 0, v[204:205]
	s_add_i32 m0, s65, 0x2000
	s_nop 0
	global_load_lds_dwordx4 v[218:219], off
	s_barrier
	s_waitcnt lgkmcnt(0)
	s_setprio 1
	s_waitcnt lgkmcnt(0)
	v_mfma_f32_16x16x32_bf16 v[128:131], v[180:183], v[148:151], v[128:131]
	v_mfma_f32_16x16x32_bf16 v[124:127], v[188:191], v[148:151], v[124:127]
	v_mfma_f32_16x16x32_bf16 v[120:123], v[180:183], v[156:159], v[120:123]
	v_mfma_f32_16x16x32_bf16 v[116:119], v[188:191], v[156:159], v[116:119]
	v_mfma_f32_16x16x32_bf16 v[112:115], v[180:183], v[164:167], v[112:115]
	v_mfma_f32_16x16x32_bf16 v[108:111], v[188:191], v[164:167], v[108:111]
	v_mfma_f32_16x16x32_bf16 v[104:107], v[180:183], v[172:175], v[104:107]
	v_mfma_f32_16x16x32_bf16 v[100:103], v[188:191], v[172:175], v[100:103]
	v_mfma_f32_16x16x32_bf16 v[128:131], v[184:187], v[152:155], v[128:131]
	v_mfma_f32_16x16x32_bf16 v[124:127], v[192:195], v[152:155], v[124:127]
	v_mfma_f32_16x16x32_bf16 v[120:123], v[184:187], v[160:163], v[120:123]
	v_mfma_f32_16x16x32_bf16 v[116:119], v[192:195], v[160:163], v[116:119]
	v_mfma_f32_16x16x32_bf16 v[112:115], v[184:187], v[168:171], v[112:115]
	v_mfma_f32_16x16x32_bf16 v[108:111], v[192:195], v[168:171], v[108:111]
	v_mfma_f32_16x16x32_bf16 v[104:107], v[184:187], v[176:179], v[104:107]
	v_mfma_f32_16x16x32_bf16 v[100:103], v[192:195], v[176:179], v[100:103]
	s_setprio 0
	s_mov_b32 m0, s42
	v_lshl_add_u64 v[220:221], s[28:29], 0, v[198:199]
	s_barrier
	ds_read_b128 v[148:151], v228 offset:16384
	ds_read_b128 v[152:155], v228 offset:17408
	ds_read_b128 v[156:159], v228 offset:18432
	ds_read_b128 v[160:163], v228 offset:19456
	ds_read_b128 v[164:167], v228 offset:20480
	ds_read_b128 v[168:171], v228 offset:21504
	ds_read_b128 v[172:175], v228 offset:22528
	ds_read_b128 v[176:179], v228 offset:23552
	global_load_lds_dwordx4 v[220:221], off
	v_lshl_add_u64 v[222:223], s[28:29], 0, v[202:203]
	s_mov_b32 m0, s43
	s_nop 0
	global_load_lds_dwordx4 v[222:223], off
	s_barrier
	s_waitcnt lgkmcnt(0)
	s_setprio 1
	s_waitcnt lgkmcnt(0)
	v_mfma_f32_16x16x32_bf16 v[96:99], v[132:135], v[148:151], v[96:99]
	v_mfma_f32_16x16x32_bf16 v[92:95], v[140:143], v[148:151], v[92:95]
	v_mfma_f32_16x16x32_bf16 v[88:91], v[132:135], v[156:159], v[88:91]
	v_mfma_f32_16x16x32_bf16 v[84:87], v[140:143], v[156:159], v[84:87]
	v_mfma_f32_16x16x32_bf16 v[80:83], v[132:135], v[164:167], v[80:83]
	v_mfma_f32_16x16x32_bf16 v[76:79], v[140:143], v[164:167], v[76:79]
	v_mfma_f32_16x16x32_bf16 v[72:75], v[132:135], v[172:175], v[72:75]
	v_mfma_f32_16x16x32_bf16 v[68:71], v[140:143], v[172:175], v[68:71]
	v_mfma_f32_16x16x32_bf16 v[96:99], v[136:139], v[152:155], v[96:99]
	v_mfma_f32_16x16x32_bf16 v[92:95], v[144:147], v[152:155], v[92:95]
	v_mfma_f32_16x16x32_bf16 v[88:91], v[136:139], v[160:163], v[88:91]
	v_mfma_f32_16x16x32_bf16 v[84:87], v[144:147], v[160:163], v[84:87]
	v_mfma_f32_16x16x32_bf16 v[80:83], v[136:139], v[168:171], v[80:83]
	v_mfma_f32_16x16x32_bf16 v[76:79], v[144:147], v[168:171], v[76:79]
	v_mfma_f32_16x16x32_bf16 v[72:75], v[136:139], v[176:179], v[72:75]
	v_mfma_f32_16x16x32_bf16 v[68:71], v[144:147], v[176:179], v[68:71]
	s_setprio 0
	s_barrier
; #define PG8_STAGE(bufoff, gbase, voff) do { _Pragma("unroll") for (int _i = 0; _i < 2; ++_i) \
;         __builtin_amdgcn_global_load_lds((const unsigned*)((const char*)(gbase) + (voff)[_i]), (LAS unsigned*)(lds + (bufoff) + ldsw + _i * 8192), 16, 0, 0); } while (0)
; #define PG8_LDA(dst, b, h) do { _Pragma("unroll") for (int m = 0; m < 4; ++m) _Pragma("unroll") for (int k = 0; k < 2; ++k) dst[m][k] = *(const LAS bf16x8*)(lds + PG8_SA(b, h) + aoff + m * 2048 + k * 1024); } while (0)
; #define PG8_LDB(dst, b, h) do { _Pragma("unroll") for (int n = 0; n < 2; ++n) _Pragma("unroll") for (int k = 0; k < 2; ++k) dst[n][k] = *(const LAS bf16x8*)(lds + PG8_SB(b, h) + boff + n * 2048 + k * 1024); } while (0)
; #define PG8_MMA(ai, bj, At, Bt) do { __builtin_amdgcn_s_setprio(1); _Pragma("unroll") for (int m = 0; m < 4; ++m) _Pragma("unroll") for (int n = 0; n < 2; ++n) _Pragma("unroll") for (int k = 0; k < 2; ++k) \
;         acc[ai][bj][m][n] = __builtin_amdgcn_mfma_f32_16x16x32_bf16(Bt[n][k], At[m][k], acc[ai][bj][m][n], 0, 0, 0); __builtin_amdgcn_s_setprio(0); } while (0)
; #define PG8_WAIT_V(n) asm volatile("s_waitcnt vmcnt(" #n ")" ::: "memory")
; #define PG8_WAIT_L(n) asm volatile("s_waitcnt lgkmcnt(" #n ")" ::: "memory")
; #define PG8_BAR __builtin_amdgcn_s_barrier()
; #define PG8_SCHED __builtin_amdgcn_sched_barrier(0)
; template <class Epi, class Sched>
; DI void gemm_phase(LAS unsigned char* lds, const Gemm g, const Sched& S, const Epi& E) {
;     ...
;             PG8_WAIT_V(6); PG8_BAR; PG8_MMA(1, 1, At, B1); PG8_BAR;
;             PG8_LDB(B0, 1, 0); PG8_SCHED; PG8_LDA(At, 1, 0); PG8_STAGE(PG8_SA(0, 1), a2 + hstep, voffA);
;             PG8_WAIT_L(8); PG8_BAR; PG8_WAIT_L(0); PG8_MMA(0, 0, At, B0); PG8_BAR; PG8_SCHED;
;             PG8_LDB(B1, 1, 1); PG8_STAGE(PG8_SB(1, 0), b3, voffB);
;             PG8_BAR; PG8_WAIT_L(0); PG8_MMA(0, 1, At, B1); PG8_BAR;
;             PG8_LDA(At, 1, 1); PG8_STAGE(PG8_SA(1, 0), a3, voffA);
;             PG8_BAR; PG8_WAIT_L(0); PG8_MMA(1, 0, At, B0); PG8_BAR; PG8_SCHED;
	s_add_u32 s66, s26, 0x80000
	s_addc_u32 s67, s27, 0
	s_add_i32 s65, s60, s41
	v_lshl_add_u64 v[6:7], s[66:67], 0, v[200:201]
	s_mov_b32 m0, s65
	s_nop 0
	global_load_lds_dwordx4 v[6:7], off
	v_lshl_add_u64 v[6:7], s[66:67], 0, v[204:205]
	s_add_i32 m0, s65, 0x2000
	s_nop 0
	global_load_lds_dwordx4 v[6:7], off
	s_waitcnt vmcnt(6)
	s_barrier
	s_setprio 1
	v_mfma_f32_16x16x32_bf16 v[64:67], v[180:183], v[148:151], v[64:67]
	v_mfma_f32_16x16x32_bf16 v[60:63], v[188:191], v[148:151], v[60:63]
	v_mfma_f32_16x16x32_bf16 v[56:59], v[180:183], v[156:159], v[56:59]
	v_mfma_f32_16x16x32_bf16 v[52:55], v[188:191], v[156:159], v[52:55]
	v_mfma_f32_16x16x32_bf16 v[48:51], v[180:183], v[164:167], v[48:51]
	v_mfma_f32_16x16x32_bf16 v[44:47], v[188:191], v[164:167], v[44:47]
	v_mfma_f32_16x16x32_bf16 v[40:43], v[180:183], v[172:175], v[40:43]
	v_mfma_f32_16x16x32_bf16 v[36:39], v[188:191], v[172:175], v[36:39]
	v_mfma_f32_16x16x32_bf16 v[64:67], v[184:187], v[152:155], v[64:67]
	v_mfma_f32_16x16x32_bf16 v[60:63], v[192:195], v[152:155], v[60:63]
	v_mfma_f32_16x16x32_bf16 v[56:59], v[184:187], v[160:163], v[56:59]
	v_mfma_f32_16x16x32_bf16 v[52:55], v[192:195], v[160:163], v[52:55]
	v_mfma_f32_16x16x32_bf16 v[48:51], v[184:187], v[168:171], v[48:51]
	v_mfma_f32_16x16x32_bf16 v[44:47], v[192:195], v[168:171], v[44:47]
	v_mfma_f32_16x16x32_bf16 v[40:43], v[184:187], v[176:179], v[40:43]
	v_mfma_f32_16x16x32_bf16 v[36:39], v[192:195], v[176:179], v[36:39]
	s_setprio 0
	s_add_i32 s65, 0, 0x18000
	v_add_u32_e32 v1, s65, v226
	s_barrier
	ds_read_b128 v[132:135], v1
	ds_read_b128 v[136:139], v1 offset:1024
	ds_read_b128 v[140:143], v1 offset:2048
	ds_read_b128 v[144:147], v1 offset:3072
	s_add_u32 s28, s28, 0x80000
	s_addc_u32 s29, s29, 0
	s_mov_b32 m0, s44
	v_lshl_add_u64 v[6:7], s[28:29], 0, v[198:199]
	ds_read_b128 v[148:151], v228 offset:32768
	ds_read_b128 v[152:155], v228 offset:33792
	ds_read_b128 v[156:159], v228 offset:34816
	ds_read_b128 v[160:163], v228 offset:35840
	ds_read_b128 v[164:167], v228 offset:36864
	ds_read_b128 v[168:171], v228 offset:37888
	ds_read_b128 v[172:175], v228 offset:38912
	ds_read_b128 v[176:179], v228 offset:39936
	global_load_lds_dwordx4 v[6:7], off
	v_lshl_add_u64 v[6:7], s[28:29], 0, v[202:203]
	s_mov_b32 m0, s45
	s_nop 0
	global_load_lds_dwordx4 v[6:7], off
	s_waitcnt lgkmcnt(8)
	s_barrier
	s_waitcnt lgkmcnt(0)
	s_setprio 1
	s_waitcnt lgkmcnt(0)
	v_mfma_f32_16x16x32_bf16 v[32:35], v[132:135], v[148:151], v[32:35]
	v_mfma_f32_16x16x32_bf16 v[28:31], v[140:143], v[148:151], v[28:31]
	v_mfma_f32_16x16x32_bf16 v[24:27], v[132:135], v[156:159], v[24:27]
	v_mfma_f32_16x16x32_bf16 v[20:23], v[140:143], v[156:159], v[20:23]
	v_mfma_f32_16x16x32_bf16 v[16:19], v[132:135], v[164:167], v[16:19]
	v_mfma_f32_16x16x32_bf16 v[12:15], v[140:143], v[164:167], v[12:15]
	v_mfma_f32_16x16x32_bf16 v[6:9], v[132:135], v[172:175], v[8:11]
	v_mfma_f32_16x16x32_bf16 v[2:5], v[140:143], v[172:175], v[2:5]
	v_mfma_f32_16x16x32_bf16 v[32:35], v[136:139], v[152:155], v[32:35]
	v_mfma_f32_16x16x32_bf16 v[28:31], v[144:147], v[152:155], v[28:31]
	v_mfma_f32_16x16x32_bf16 v[24:27], v[136:139], v[160:163], v[24:27]
	v_mfma_f32_16x16x32_bf16 v[20:23], v[144:147], v[160:163], v[20:23]
	v_mfma_f32_16x16x32_bf16 v[16:19], v[136:139], v[168:171], v[16:19]
	v_mfma_f32_16x16x32_bf16 v[12:15], v[144:147], v[168:171], v[12:15]
	v_mfma_f32_16x16x32_bf16 v[8:11], v[136:139], v[176:179], v[6:9]
	v_mfma_f32_16x16x32_bf16 v[4:7], v[144:147], v[176:179], v[2:5]
	s_setprio 0
	s_barrier
	s_add_i32 s28, 0, 0x1c000
	s_add_i32 s29, s65, s41
	v_add_u32_e32 v1, s28, v226
	v_lshl_add_u64 v[2:3], v[216:217], 0, s[14:15]
	s_mov_b32 m0, s29
	ds_read_b128 v[180:183], v1
	ds_read_b128 v[184:187], v1 offset:1024
	ds_read_b128 v[188:191], v1 offset:2048
	ds_read_b128 v[192:195], v1 offset:3072
	global_load_lds_dwordx4 v[2:3], off
	v_lshl_add_u64 v[2:3], v[218:219], 0, s[14:15]
	s_add_i32 m0, s29, 0x2000
	s_nop 0
	global_load_lds_dwordx4 v[2:3], off
	s_barrier
	s_waitcnt lgkmcnt(0)
	s_setprio 1
	s_waitcnt lgkmcnt(0)
	v_mfma_f32_16x16x32_bf16 v[128:131], v[180:183], v[148:151], v[128:131]
	v_mfma_f32_16x16x32_bf16 v[124:127], v[188:191], v[148:151], v[124:127]
	v_mfma_f32_16x16x32_bf16 v[120:123], v[180:183], v[156:159], v[120:123]
	v_mfma_f32_16x16x32_bf16 v[116:119], v[188:191], v[156:159], v[116:119]
	v_mfma_f32_16x16x32_bf16 v[112:115], v[180:183], v[164:167], v[112:115]
	v_mfma_f32_16x16x32_bf16 v[108:111], v[188:191], v[164:167], v[108:111]
	v_mfma_f32_16x16x32_bf16 v[104:107], v[180:183], v[172:175], v[104:107]
	v_mfma_f32_16x16x32_bf16 v[100:103], v[188:191], v[172:175], v[100:103]
	v_mfma_f32_16x16x32_bf16 v[128:131], v[184:187], v[152:155], v[128:131]
	v_mfma_f32_16x16x32_bf16 v[124:127], v[192:195], v[152:155], v[124:127]
	v_mfma_f32_16x16x32_bf16 v[120:123], v[184:187], v[160:163], v[120:123]
	v_mfma_f32_16x16x32_bf16 v[116:119], v[192:195], v[160:163], v[116:119]
	v_mfma_f32_16x16x32_bf16 v[112:115], v[184:187], v[168:171], v[112:115]
	v_mfma_f32_16x16x32_bf16 v[108:111], v[192:195], v[168:171], v[108:111]
	v_mfma_f32_16x16x32_bf16 v[104:107], v[184:187], v[176:179], v[104:107]
	v_mfma_f32_16x16x32_bf16 v[100:103], v[192:195], v[176:179], v[100:103]
	s_setprio 0
	s_mov_b32 m0, s58
	v_lshl_add_u64 v[2:3], v[220:221], 0, s[14:15]
	s_barrier
	ds_read_b128 v[148:151], v228 offset:49152
	ds_read_b128 v[152:155], v228 offset:50176
	ds_read_b128 v[156:159], v228 offset:51200
	ds_read_b128 v[160:163], v228 offset:52224
	ds_read_b128 v[164:167], v228 offset:53248
	ds_read_b128 v[168:171], v228 offset:54272
	ds_read_b128 v[172:175], v228 offset:55296
	ds_read_b128 v[176:179], v228 offset:56320
	global_load_lds_dwordx4 v[2:3], off
	v_lshl_add_u64 v[2:3], v[222:223], 0, s[14:15]
	s_mov_b32 m0, s59
	s_nop 0
	global_load_lds_dwordx4 v[2:3], off
	s_barrier
; DI size_t pix(int row, int col) { return ((size_t)(col >> 8) * MROWS + (size_t)row) * 256 + (size_t)(col & 255); }
; #define PG8_STAGE(bufoff, gbase, voff) do { _Pragma("unroll") for (int _i = 0; _i < 2; ++_i) \
;         __builtin_amdgcn_global_load_lds((const unsigned*)((const char*)(gbase) + (voff)[_i]), (LAS unsigned*)(lds + (bufoff) + ldsw + _i * 8192), 16, 0, 0); } while (0)
; #define PG8_MMA(ai, bj, At, Bt) do { __builtin_amdgcn_s_setprio(1); _Pragma("unroll") for (int m = 0; m < 4; ++m) _Pragma("unroll") for (int n = 0; n < 2; ++n) _Pragma("unroll") for (int k = 0; k < 2; ++k) \
;         acc[ai][bj][m][n] = __builtin_amdgcn_mfma_f32_16x16x32_bf16(Bt[n][k], At[m][k], acc[ai][bj][m][n], 0, 0, 0); __builtin_amdgcn_s_setprio(0); } while (0)
; #define PG8_WAIT_V(n) asm volatile("s_waitcnt vmcnt(" #n ")" ::: "memory")
; #define PG8_BAR __builtin_amdgcn_s_barrier()
; template <class Epi, class Sched>
; DI void gemm_phase(LAS unsigned char* lds, const Gemm g, const Sched& S, const Epi& E) {
;     ...
;             PG8_STAGE(PG8_SB(1, 1), b3 + hstep, voffB);
;             PG8_WAIT_V(6); PG8_BAR; PG8_MMA(1, 1, At, B1); PG8_BAR;
;     DI bool operator()(f32x4 (&acc)[2][2][4][2], const pg8::Unit& u, int wr, int wc, int fr, int fq) const {
;     ...
;             u32x4 gbv[4][2], gav[4][2];
; #pragma unroll
;             for (int m = 0; m < 4; ++m) { const int row = row0 + ai * 128 + m * 16;
;                 const bf16_t* pgb = P + pix(row, C_GB + col0); const bf16_t* pga = P + pix(row, C_GA + col0);
; #pragma unroll
;                 for (int bj = 0; bj < 2; ++bj) { gbv[m][bj] = *(const u32x4*)(pgb + bj * 128); if (z0) gav[m][bj] = *(const u32x4*)(pga + bj * 128); else gav[m][bj] = gbv[m][bj]; } }
;             __builtin_amdgcn_sched_barrier(0);
	s_waitcnt lgkmcnt(0)
	s_setprio 1
	s_waitcnt lgkmcnt(0)
	v_mfma_f32_16x16x32_bf16 v[96:99], v[132:135], v[148:151], v[96:99]
	v_mfma_f32_16x16x32_bf16 v[92:95], v[140:143], v[148:151], v[92:95]
	v_mfma_f32_16x16x32_bf16 v[88:91], v[132:135], v[156:159], v[88:91]
	v_mfma_f32_16x16x32_bf16 v[84:87], v[140:143], v[156:159], v[84:87]
	v_mfma_f32_16x16x32_bf16 v[80:83], v[132:135], v[164:167], v[80:83]
	v_mfma_f32_16x16x32_bf16 v[76:79], v[140:143], v[164:167], v[76:79]
	v_mfma_f32_16x16x32_bf16 v[72:75], v[132:135], v[172:175], v[72:75]
	v_mfma_f32_16x16x32_bf16 v[68:71], v[140:143], v[172:175], v[68:71]
	v_mfma_f32_16x16x32_bf16 v[96:99], v[136:139], v[152:155], v[96:99]
	v_mfma_f32_16x16x32_bf16 v[92:95], v[144:147], v[152:155], v[92:95]
	v_mfma_f32_16x16x32_bf16 v[88:91], v[136:139], v[160:163], v[88:91]
	v_mfma_f32_16x16x32_bf16 v[84:87], v[144:147], v[160:163], v[84:87]
	v_mfma_f32_16x16x32_bf16 v[80:83], v[136:139], v[168:171], v[80:83]
	v_mfma_f32_16x16x32_bf16 v[76:79], v[144:147], v[168:171], v[76:79]
	v_mfma_f32_16x16x32_bf16 v[72:75], v[136:139], v[176:179], v[72:75]
	v_mfma_f32_16x16x32_bf16 v[68:71], v[144:147], v[176:179], v[68:71]
	s_setprio 0
	s_barrier
	s_add_u32 s26, s26, 0x80080
	s_addc_u32 s27, s27, 0
	s_add_i32 s28, s28, s41
	v_lshl_add_u64 v[2:3], s[26:27], 0, v[200:201]
	s_mov_b32 m0, s28
	s_nop 0
	global_load_lds_dwordx4 v[2:3], off
	v_lshl_add_u64 v[2:3], s[26:27], 0, v[204:205]
	s_add_i32 m0, s28, 0x2000
	s_nop 0
	global_load_lds_dwordx4 v[2:3], off
	s_waitcnt vmcnt(6)
	s_barrier
	s_setprio 1
	v_mfma_f32_16x16x32_bf16 v[64:67], v[180:183], v[148:151], v[64:67]
	v_mfma_f32_16x16x32_bf16 v[60:63], v[188:191], v[148:151], v[60:63]
	v_mfma_f32_16x16x32_bf16 v[56:59], v[180:183], v[156:159], v[56:59]
	v_mfma_f32_16x16x32_bf16 v[52:55], v[188:191], v[156:159], v[52:55]
	v_mfma_f32_16x16x32_bf16 v[48:51], v[180:183], v[164:167], v[48:51]
	v_mfma_f32_16x16x32_bf16 v[44:47], v[188:191], v[164:167], v[44:47]
	v_mfma_f32_16x16x32_bf16 v[40:43], v[180:183], v[172:175], v[40:43]
	v_mfma_f32_16x16x32_bf16 v[36:39], v[188:191], v[172:175], v[36:39]
	v_mfma_f32_16x16x32_bf16 v[64:67], v[184:187], v[152:155], v[64:67]
	v_mfma_f32_16x16x32_bf16 v[60:63], v[192:195], v[152:155], v[60:63]
	v_mfma_f32_16x16x32_bf16 v[56:59], v[184:187], v[160:163], v[56:59]
	v_mfma_f32_16x16x32_bf16 v[52:55], v[192:195], v[160:163], v[52:55]
	v_mfma_f32_16x16x32_bf16 v[48:51], v[184:187], v[168:171], v[48:51]
	v_mfma_f32_16x16x32_bf16 v[44:47], v[192:195], v[168:171], v[44:47]
	v_mfma_f32_16x16x32_bf16 v[40:43], v[184:187], v[176:179], v[40:43]
	v_mfma_f32_16x16x32_bf16 v[36:39], v[192:195], v[176:179], v[36:39]
	s_setprio 0
	s_add_i32 s64, s64, 2
	s_add_u32 s24, s24, 0x100
	s_addc_u32 s25, s25, 0
	s_add_u32 s31, s31, 0x100
	s_addc_u32 s63, s63, 0
	s_cmp_gt_u32 s64, 29
	s_barrier
	s_cbranch_scc0 .LBB0_726
	s_lshl_b32 s17, s6, 8
	s_cmp_eq_u32 s7, 0
	v_lshl_add_u32 v216, s4, 8, v197
	s_cselect_b64 s[4:5], -1, 0
	s_cmp_lg_u32 s7, 0
	s_cselect_b64 s[28:29], -1, 0
	s_add_i32 s6, s17, 0x5800
	s_ashr_i32 s24, s6, 8
	v_ashrrev_i32_e32 v217, 31, v216
	v_mad_i64_i32 v[2:3], s[6:7], s24, v229, v[216:217]
	v_lshlrev_b64 v[2:3], 9, v[2:3]
	v_lshl_add_u64 v[2:3], v[206:207], 0, v[2:3]
	global_load_dwordx4 v[192:195], v[2:3], off
	s_add_i32 s6, s17, 0x4800
	s_ashr_i32 s19, s6, 8
	v_mad_i64_i32 v[132:133], s[6:7], s19, v229, v[216:217]
	v_lshlrev_b64 v[132:133], 9, v[132:133]
	s_and_b64 vcc, exec, s[28:29]
	v_lshl_add_u64 v[132:133], v[206:207], 0, v[132:133]
	s_cbranch_vccnz .LBB0_729
	global_load_dwordx4 v[188:191], v[132:133], off
.LBB0_729:
	global_load_dwordx4 v[184:187], v[2:3], off offset:256
	v_cndmask_b32_e64 v1, 0, 1, s[4:5]
	v_cmp_ne_u32_e64 s[6:7], 1, v1
	s_andn2_b64 vcc, exec, s[4:5]
	s_cbranch_vccnz .LBB0_731
	global_load_dwordx4 v[180:183], v[132:133], off offset:256
.LBB0_731:
	v_or_b32_e32 v222, 16, v216
	s_mul_hi_i32 s25, s24, 0x4200
	s_mulk_i32 s24, 0x4200
	v_ashrrev_i32_e32 v223, 31, v222
	v_lshl_add_u64 v[2:3], s[24:25], 0, v[222:223]
	v_lshlrev_b64 v[2:3], 9, v[2:3]
	v_lshl_add_u64 v[2:3], v[206:207], 0, v[2:3]
	global_load_dwordx4 v[176:179], v[2:3], off
	s_mul_hi_i32 s27, s19, 0x4200
	s_mul_i32 s26, s19, 0x4200
	v_lshl_add_u64 v[132:133], s[26:27], 0, v[222:223]
	v_lshlrev_b64 v[132:133], 9, v[132:133]
	v_lshl_add_u64 v[132:133], v[206:207], 0, v[132:133]
	s_and_b64 vcc, exec, s[6:7]
	s_cbranch_vccnz .LBB0_733
	global_load_dwordx4 v[172:175], v[132:133], off
.LBB0_733:
	global_load_dwordx4 v[168:171], v[2:3], off offset:256
	s_and_b64 vcc, exec, s[6:7]
	s_cbranch_vccnz .LBB0_735
	global_load_dwordx4 v[164:167], v[132:133], off offset:256
.LBB0_735:
	v_or_b32_e32 v220, 32, v216
	v_ashrrev_i32_e32 v221, 31, v220
	v_lshl_add_u64 v[2:3], s[24:25], 0, v[220:221]
	v_lshlrev_b64 v[2:3], 9, v[2:3]
	v_lshl_add_u64 v[2:3], v[206:207], 0, v[2:3]
	global_load_dwordx4 v[160:163], v[2:3], off
	v_lshl_add_u64 v[132:133], s[26:27], 0, v[220:221]
	v_lshlrev_b64 v[132:133], 9, v[132:133]
	v_lshl_add_u64 v[132:133], v[206:207], 0, v[132:133]
	s_and_b64 vcc, exec, s[6:7]
	s_cbranch_vccnz .LBB0_737
	global_load_dwordx4 v[156:159], v[132:133], off
.LBB0_737:
	global_load_dwordx4 v[152:155], v[2:3], off offset:256
	s_and_b64 vcc, exec, s[6:7]
	s_cbranch_vccnz .LBB0_739
	global_load_dwordx4 v[148:151], v[132:133], off offset:256
.LBB0_739:
	v_or_b32_e32 v218, 48, v216
	v_ashrrev_i32_e32 v219, 31, v218
	v_lshl_add_u64 v[2:3], s[24:25], 0, v[218:219]
	v_lshlrev_b64 v[2:3], 9, v[2:3]
	v_lshl_add_u64 v[2:3], v[206:207], 0, v[2:3]
	global_load_dwordx4 v[144:147], v[2:3], off
	v_lshl_add_u64 v[132:133], s[26:27], 0, v[218:219]
	v_lshlrev_b64 v[132:133], 9, v[132:133]
	v_lshl_add_u64 v[224:225], v[206:207], 0, v[132:133]
	s_and_b64 vcc, exec, s[6:7]
	s_cbranch_vccnz .LBB0_741
	global_load_dwordx4 v[140:143], v[224:225], off
.LBB0_741:
	global_load_dwordx4 v[136:139], v[2:3], off offset:256
	s_and_b64 vcc, exec, s[6:7]
	s_cbranch_vccnz .LBB0_743
	global_load_dwordx4 v[132:135], v[224:225], off offset:256
.LBB0_743:
	s_waitcnt vmcnt(0)
	s_and_b64 vcc, exec, s[6:7]
	s_cbranch_vccz .Lepm_nc_0
	v_mov_b64_e32 v[188:189], v[192:193]
	v_mov_b64_e32 v[190:191], v[194:195]
	v_mov_b64_e32 v[180:181], v[184:185]
	v_mov_b64_e32 v[182:183], v[186:187]
	v_mov_b64_e32 v[172:173], v[176:177]
	v_mov_b64_e32 v[174:175], v[178:179]
	v_mov_b64_e32 v[164:165], v[168:169]
	v_mov_b64_e32 v[166:167], v[170:171]
	v_mov_b64_e32 v[156:157], v[160:161]
	v_mov_b64_e32 v[158:159], v[162:163]
	v_mov_b64_e32 v[148:149], v[152:153]
	v_mov_b64_e32 v[150:151], v[154:155]
	v_mov_b64_e32 v[140:141], v[144:145]
	v_mov_b64_e32 v[142:143], v[146:147]
	v_mov_b64_e32 v[132:133], v[136:137]
	v_mov_b64_e32 v[134:135], v[138:139]

; DI size_t pix(int row, int col) { return ((size_t)(col >> 8) * MROWS + (size_t)row) * 256 + (size_t)(col & 255); }
;     DI bool operator()(f32x4 (&acc)[2][2][4][2], const pg8::Unit& u, int wr, int wc, int fr, int fq) const {
;     ...
;             u32x4 gbv[4][2], gav[4][2];
; #pragma unroll
;             for (int m = 0; m < 4; ++m) { const int row = row0 + ai * 128 + m * 16;
;                 const bf16_t* pgb = P + pix(row, C_GB + col0); const bf16_t* pga = P + pix(row, C_GA + col0);
; #pragma unroll
;                 for (int bj = 0; bj < 2; ++bj) { gbv[m][bj] = *(const u32x4*)(pgb + bj * 128); if (z0) gav[m][bj] = *(const u32x4*)(pga + bj * 128); else gav[m][bj] = gbv[m][bj]; } }
.LBB0_775:
	v_add_u32_e32 v222, 0x80, v216
	v_ashrrev_i32_e32 v223, 31, v222
	s_waitcnt vmcnt(0)
	v_lshl_add_u64 v[132:133], s[24:25], 0, v[222:223]
	v_lshlrev_b64 v[132:133], 9, v[132:133]
	v_lshl_add_u64 v[132:133], v[206:207], 0, v[132:133]
	global_load_dwordx4 v[192:195], v[132:133], off
	v_lshl_add_u64 v[134:135], s[26:27], 0, v[222:223]
	v_lshlrev_b64 v[134:135], 9, v[134:135]
	v_lshl_add_u64 v[134:135], v[206:207], 0, v[134:135]
	s_and_b64 vcc, exec, s[6:7]
	s_cbranch_vccnz .LBB0_777
	global_load_dwordx4 v[188:191], v[134:135], off
.LBB0_777:
	global_load_dwordx4 v[184:187], v[132:133], off offset:256
	s_and_b64 vcc, exec, s[6:7]
	s_cbranch_vccnz .LBB0_779
	global_load_dwordx4 v[180:183], v[134:135], off offset:256
.LBB0_779:
	v_add_u32_e32 v220, 0x90, v216
	v_ashrrev_i32_e32 v221, 31, v220
	v_lshl_add_u64 v[132:133], s[24:25], 0, v[220:221]
	v_lshlrev_b64 v[132:133], 9, v[132:133]
	v_lshl_add_u64 v[132:133], v[206:207], 0, v[132:133]
	global_load_dwordx4 v[176:179], v[132:133], off
	v_lshl_add_u64 v[134:135], s[26:27], 0, v[220:221]
	v_lshlrev_b64 v[134:135], 9, v[134:135]
	v_lshl_add_u64 v[134:135], v[206:207], 0, v[134:135]
	s_and_b64 vcc, exec, s[6:7]
	s_cbranch_vccnz .LBB0_781
	global_load_dwordx4 v[172:175], v[134:135], off
.LBB0_781:
	global_load_dwordx4 v[168:171], v[132:133], off offset:256
	s_and_b64 vcc, exec, s[6:7]
	s_cbranch_vccnz .LBB0_783
	global_load_dwordx4 v[164:167], v[134:135], off offset:256
.LBB0_783:
	v_add_u32_e32 v218, 0xa0, v216
	v_ashrrev_i32_e32 v219, 31, v218
	v_lshl_add_u64 v[132:133], s[24:25], 0, v[218:219]
	v_lshlrev_b64 v[132:133], 9, v[132:133]
	v_lshl_add_u64 v[132:133], v[206:207], 0, v[132:133]
	global_load_dwordx4 v[160:163], v[132:133], off
	v_lshl_add_u64 v[134:135], s[26:27], 0, v[218:219]
	v_lshlrev_b64 v[134:135], 9, v[134:135]
	v_lshl_add_u64 v[134:135], v[206:207], 0, v[134:135]
	s_and_b64 vcc, exec, s[6:7]
	s_cbranch_vccnz .LBB0_785
	global_load_dwordx4 v[156:159], v[134:135], off
.LBB0_785:
	global_load_dwordx4 v[152:155], v[132:133], off offset:256
	s_and_b64 vcc, exec, s[6:7]
	s_cbranch_vccnz .LBB0_787
	global_load_dwordx4 v[148:151], v[134:135], off offset:256
.LBB0_787:
	v_add_u32_e32 v216, 0xb0, v216
	v_ashrrev_i32_e32 v217, 31, v216
	v_lshl_add_u64 v[132:133], s[24:25], 0, v[216:217]
	v_lshlrev_b64 v[132:133], 9, v[132:133]
	v_lshl_add_u64 v[132:133], v[206:207], 0, v[132:133]
	global_load_dwordx4 v[144:147], v[132:133], off
	v_lshl_add_u64 v[134:135], s[26:27], 0, v[216:217]
	v_lshlrev_b64 v[134:135], 9, v[134:135]
	v_lshl_add_u64 v[224:225], v[206:207], 0, v[134:135]
	s_and_b64 vcc, exec, s[6:7]
	s_cbranch_vccnz .LBB0_789
	global_load_dwordx4 v[140:143], v[224:225], off
.LBB0_789:
	global_load_dwordx4 v[136:139], v[132:133], off offset:256
	s_and_b64 vcc, exec, s[6:7]
	s_cbranch_vccnz .LBB0_791
	global_load_dwordx4 v[132:135], v[224:225], off offset:256
